# combination + w_in item permutation in P0(a) + static wave priority in GEMM tiles
# speedup vs baseline: 1.0078x; 1.0078x over previous
.LBB0_620:
	s_setprio 0
	v_readlane_b32 s80, v242, 21
	v_lshlrev_b32_e32 v114, 3, v158
	v_or_b32_e32 v115, s47, v148
	v_readlane_b32 s81, v242, 22
	v_add_u32_e32 v150, s35, v115
	v_lshl_or_b32 v114, s12, 5, v114
	v_readlane_b32 s82, v242, 23
	v_readlane_b32 s83, v242, 24
	s_mov_b64 s[36:37], s[80:81]
	v_or_b32_e32 v148, s34, v114
	v_add_u32_e32 v114, 0xffffc000, v150
	v_ashrrev_i32_e32 v151, 31, v150
	v_cmp_gt_i32_e32 vcc, s45, v150
	s_mov_b64 s[38:39], s[82:83]
	v_mov_b32_e32 v118, s39
	v_cndmask_b32_e32 v115, 0, v151, vcc
	v_cndmask_b32_e32 v114, v114, v150, vcc
	v_mov_b32_e32 v119, s37
	v_mov_b32_e32 v120, s38
	v_mov_b32_e32 v121, s36
	v_ashrrev_i32_e32 v149, 31, v148
	v_cndmask_b32_e32 v117, v118, v119, vcc
	v_cndmask_b32_e32 v116, v120, v121, vcc
	v_lshlrev_b64 v[114:115], 12, v[114:115]
	v_lshl_add_u64 v[114:115], v[116:117], 0, v[114:115]
	v_lshlrev_b64 v[152:153], 2, v[148:149]
	v_lshl_add_u64 v[114:115], v[114:115], 0, v[152:153]
	v_mov_b32_e32 v176, v114
	v_mov_b32_e32 v177, v115
	global_load_dwordx4 v[160:163], v[114:115], off
	global_load_dwordx4 v[164:167], v[114:115], off offset:16
	global_load_dwordx4 v[168:171], v[114:115], off offset:512
	global_load_dwordx4 v[172:175], v[114:115], off offset:528
	v_or_b32_e32 v154, 16, v150
	v_add_u32_e32 v114, 0xffffc010, v150
	v_ashrrev_i32_e32 v155, 31, v154
	v_cmp_gt_i32_e32 vcc, s45, v154
	v_readlane_b32 s84, v242, 25
	v_readlane_b32 s85, v242, 26
	v_cndmask_b32_e32 v115, 0, v155, vcc
	v_cndmask_b32_e32 v114, v114, v154, vcc
	v_cndmask_b32_e32 v117, v118, v119, vcc
	v_cndmask_b32_e32 v116, v120, v121, vcc
	v_lshlrev_b64 v[114:115], 12, v[114:115]
	v_lshl_add_u64 v[114:115], v[116:117], 0, v[114:115]
	v_lshl_add_u64 v[118:119], v[114:115], 0, v[152:153]
	global_load_dwordx4 v[130:133], v[118:119], off offset:16
	global_load_dwordx4 v[138:141], v[118:119], off
	global_load_dwordx4 v[114:117], v[118:119], off offset:528
	s_nop 0
	global_load_dwordx4 v[118:121], v[118:119], off offset:512
	s_mov_b64 s[96:97], 0x20000
	v_lshl_add_u64 v[178:179], v[176:177], 0, s[96:97]
	global_load_dwordx4 v[186:189], v[178:179], off
	global_load_dwordx4 v[190:193], v[178:179], off offset:16
	global_load_dwordx4 v[194:197], v[178:179], off offset:512
	global_load_dwordx4 v[198:201], v[178:179], off offset:528
	v_cmp_eq_u32_e32 vcc, 0, v158
	v_readlane_b32 s86, v242, 27
	v_readlane_b32 s87, v242, 28
	v_readlane_b32 s88, v242, 29
	v_readlane_b32 s89, v242, 30
	v_readlane_b32 s90, v242, 31
	v_readlane_b32 s91, v242, 32
	v_readlane_b32 s92, v242, 33
	v_readlane_b32 s93, v242, 34
	v_readlane_b32 s94, v242, 35
	v_readlane_b32 s95, v242, 36
	s_waitcnt vmcnt(4)
	v_pk_add_f32 v[144:145], v[144:145], v[162:163]
	v_pk_add_f32 v[142:143], v[142:143], v[160:161]
	v_pk_add_f32 v[136:137], v[136:137], v[166:167]
	v_pk_add_f32 v[134:135], v[134:135], v[164:165]
	v_pk_add_f32 v[158:159], v[128:129], v[170:171]
	v_pk_add_f32 v[160:161], v[126:127], v[168:169]
	v_pk_add_f32 v[124:125], v[124:125], v[174:175]
	v_pk_add_f32 v[122:123], v[122:123], v[172:173]
	v_cvt_pk_bf16_f32 v126, v142, v143
	v_cvt_pk_bf16_f32 v127, v144, v145
	v_cvt_pk_bf16_f32 v128, v134, v135
	v_cvt_pk_bf16_f32 v129, v136, v137
	v_cvt_pk_bf16_f32 v134, v160, v161
	v_cvt_pk_bf16_f32 v135, v158, v159
	s_nop 0
	v_cvt_pk_bf16_f32 v136, v122, v123
	v_cvt_pk_bf16_f32 v137, v124, v125
	v_and_b32_e32 v123, 0xffff0000, v126
	v_and_b32_e32 v125, 0xffff0000, v127
	v_and_b32_e32 v143, 0xffff0000, v128
	v_and_b32_e32 v145, 0xffff0000, v129
	v_and_b32_e32 v158, 0xffff0000, v134
	v_and_b32_e32 v160, 0xffff0000, v135
	v_and_b32_e32 v162, 0xffff0000, v136
	v_and_b32_e32 v164, 0xffff0000, v137
	v_lshlrev_b32_e32 v122, 16, v126
	v_lshlrev_b32_e32 v124, 16, v127
	v_lshlrev_b32_e32 v142, 16, v128
	v_lshlrev_b32_e32 v144, 16, v129
	v_lshlrev_b32_e32 v146, 16, v134
	v_lshlrev_b32_e32 v159, 16, v135
	v_lshlrev_b32_e32 v161, 16, v136
	v_lshlrev_b32_e32 v163, 16, v137
	v_mul_f32_e32 v123, v123, v123
	v_mul_f32_e32 v125, v125, v125
	v_mul_f32_e32 v143, v143, v143
	v_mul_f32_e32 v145, v145, v145
	v_mul_f32_e32 v158, v158, v158
	v_mul_f32_e32 v160, v160, v160
	v_mul_f32_e32 v162, v162, v162
	v_mul_f32_e32 v164, v164, v164
	v_fmac_f32_e32 v123, v122, v122
	v_fmac_f32_e32 v125, v124, v124
	v_fmac_f32_e32 v143, v142, v142
	v_fmac_f32_e32 v145, v144, v144
	v_fmac_f32_e32 v158, v146, v146
	v_fmac_f32_e32 v160, v159, v159
	v_fmac_f32_e32 v162, v161, v161
	v_fmac_f32_e32 v164, v163, v163
	v_add_f32_e32 v122, v123, v125
	v_add_f32_e32 v123, v143, v145
	v_add_f32_e32 v124, v158, v160
	v_add_f32_e32 v125, v162, v164
	v_add_f32_e32 v122, v122, v123
	v_add_f32_e32 v123, v124, v125
	v_and_b32_e32 v124, 64, v156
	v_add_f32_e32 v123, v122, v123
	v_xor_b32_e32 v122, 16, v156
	v_add_u32_e32 v125, 64, v124
	v_cmp_lt_i32_e64 s[4:5], v122, v125
	v_lshlrev_b64 v[142:143], 11, v[150:151]
	v_lshl_add_u64 v[142:143], s[2:3], 0, v[142:143]
	v_cndmask_b32_e64 v122, v156, v122, s[4:5]
	v_lshlrev_b32_e32 v122, 2, v122
	ds_bpermute_b32 v124, v122, v123
	s_lshr_b32 s4, s34, 6
	s_and_b32 s4, s4, 12
	s_or_b32 s34, s4, s12
	v_lshl_add_u64 v[142:143], v[148:149], 1, v[142:143]
	s_waitcnt lgkmcnt(0)
	v_add_f32_e32 v124, v123, v124
	v_xor_b32_e32 v123, 32, v156
	v_cmp_lt_i32_e64 s[4:5], v123, v125
	global_store_dwordx4 v[142:143], v[126:129], off
	global_store_dwordx4 v[142:143], v[134:137], off offset:256
	v_cndmask_b32_e64 v123, v156, v123, s[4:5]
	v_lshlrev_b32_e32 v123, 2, v123
	ds_bpermute_b32 v125, v123, v124
	s_and_saveexec_b64 s[4:5], vcc
	s_cbranch_execz .LBB0_622
	v_lshlrev_b64 v[126:127], 6, v[150:151]
	v_lshl_add_u64 v[126:127], s[8:9], 0, v[126:127]
	s_lshl_b32 s12, s34, 2
	v_lshl_add_u64 v[126:127], v[126:127], 0, s[12:13]
	s_waitcnt lgkmcnt(0)
	v_add_f32_e32 v124, v124, v125
	global_store_dword v[126:127], v124, off
